# plus: no store-drain wait ahead of the weight-conversion dequeue barrier
# speedup vs baseline: 1.0252x; 1.0004x over previous
; __device__ __forceinline__ void conv_drain(const float* const* in, unsigned char* ws, LAS unsigned char* lds, int layer, int tid) {
;     ...
;     for (;;) {
;         __syncthreads();
;         if (tid == 0) wq[0] = (int)atomicAdd(ctr, 16u);
;         __syncthreads();
.LBB0_452:
	s_nop 0
	s_barrier
	s_and_saveexec_b64 s[2:3], s[0:1]
	s_cbranch_execz .LBB0_454
	v_mov_b64_e32 v[2:3], s[4:5]
	flat_atomic_add v0, v[2:3], v223 sc0
	v_readlane_b32 s6, v253, 29
	s_nop 1
	v_mov_b32_e32 v2, s6
	s_waitcnt vmcnt(0) lgkmcnt(0)
	ds_write_b32 v2, v0
